# MLA loop: row-max exchange only on rare path, per-half-lane row sums combined at exit, merged waits, kr prefetch via SGPR base
# baseline (speedup 1.0000x reference)
; #define SLOAD() do { vs0 = *(const bf16x8*)(Vh + voff); vs1 = *(const bf16x8*)(Vh + voff + 32u * (unsigned)ldv); \
;     ks0 = *(const bf16x8*)(Kh + koff); ks1 = *(const bf16x8*)(Kh + koff + 32u * (unsigned)ldk); \
;     if constexpr (NR > 0) { kr = *(const bf16x8*)(Krh + kroff); kroff += 64u * 64u; } voff += 64u * (unsigned)ldv; koff += 64u * (unsigned)ldk; } while (0)
; #define SLOAD() do { vs0 = *(const bf16x8*)(Vh + voff); vs1 = *(const bf16x8*)(Vh + voff + 32u * (unsigned)ldv); \
;     ks0 = *(const bf16x8*)(Kh + voff); ks1 = *(const bf16x8*)(Kh + voff + 32u * (unsigned)ldv); \
;     if constexpr (NR > 0) { kr = *(const bf16x8*)(Krh + kroff); kroff += 64u * 64u; } voff += 64u * (unsigned)ldv; } while (0)
; #define SLOAD() do { vs0 = *(const bf16x8*)(Vh + voff); vs1 = *(const bf16x8*)(Vh + voff + 32u * (unsigned)ldv); kn = *(const v4i32*)(Kn8 + knoff); \
;     if (krw) kr = *(const v4i32*)(Kr8 + kroff); voff += 64u * (unsigned)ldv; knoff += 64u * (unsigned)ldk; kroff += 64u * 64u; } while (0)
; #define SLOAD() do { vt = *(const v4i32*)(VT8 + vtoff); kn = *(const v4i32*)(Kn8 + knoff); if (krw) kr = *(const v4i32*)(Kr8 + kroff); \
;     vtoff += 8192u; knoff += 64u * (unsigned)ldk; kroff += 64u * 64u; } while (0)
; __device__ __forceinline__ void attn_unit7(const unsigned char* __restrict__ Q8, int ldq, const unsigned char* __restrict__ Kn8, int ldk, const unsigned char* __restrict__ Kr8, ...
;     ...
;   for (int j = 1; j + 1 < NT; j += 2) {
;     SLOAD();
;     qkt9(pB0, pB1, Kn_lds + 8192, Kr_lds + 4096, qf, 7.0f - m_reg, r32, hi);
;     finishSM9(pA0, pA1, alA, l_reg, p8);
;     pv8(o, Vt_lds, p8, r32, hi); partialSM9(pB0, pB1, m_reg, alB, thr_raw);
.LBB0_1320:
	s_or_b64 exec, exec, s[20:21]
	v_and_b32_e32 v0, 0x3fffffc0, v12
	s_mov_b32 s20, 0x60000
	v_lshl_add_u32 v187, v0, 2, 0
	v_add3_u32 v178, v13, v14, s20
	v_add_u32_e32 v0, v15, v16
	v_mov_b32_e32 v14, v1
	v_mov_b32_e32 v15, v1
	v_and_b32_e32 v184, 63, v12
	v_lshl_add_u64 v[180:181], s[12:13], 0, v[0:1]
	v_mov_b32_e32 v0, v1
	v_mov_b32_e32 v2, v1
	v_mov_b32_e32 v3, v1
	v_mov_b32_e32 v4, v1
	v_mov_b32_e32 v5, v1
	v_mov_b32_e32 v6, v1
	v_mov_b32_e32 v7, v1
	v_mov_b32_e32 v8, v1
	v_mov_b32_e32 v9, v1
	v_mov_b32_e32 v10, v1
	v_mov_b32_e32 v11, v1
	v_mov_b32_e32 v12, v1
	v_mov_b32_e32 v13, v1
	v_mov_b64_e32 v[64:65], v[14:15]
	v_mov_b64_e32 v[48:49], v[14:15]
	v_mov_b64_e32 v[32:33], v[14:15]
	v_mov_b64_e32 v[62:63], v[12:13]
	v_mov_b64_e32 v[60:61], v[10:11]
	v_mov_b64_e32 v[58:59], v[8:9]
	v_mov_b64_e32 v[56:57], v[6:7]
	v_mov_b64_e32 v[54:55], v[4:5]
	v_mov_b64_e32 v[52:53], v[2:3]
	v_mov_b64_e32 v[50:51], v[0:1]
	v_mov_b64_e32 v[46:47], v[12:13]
	v_mov_b64_e32 v[44:45], v[10:11]
	v_mov_b64_e32 v[42:43], v[8:9]
	v_mov_b64_e32 v[40:41], v[6:7]
	v_mov_b64_e32 v[38:39], v[4:5]
	v_mov_b64_e32 v[36:37], v[2:3]
	v_mov_b64_e32 v[34:35], v[0:1]
	v_mov_b64_e32 v[30:31], v[12:13]
	v_mov_b64_e32 v[28:29], v[10:11]
	v_mov_b64_e32 v[26:27], v[8:9]
	v_mov_b64_e32 v[24:25], v[6:7]
	v_mov_b64_e32 v[22:23], v[4:5]
	v_mov_b64_e32 v[20:21], v[2:3]
	v_mov_b64_e32 v[18:19], v[0:1]
	v_mov_b64_e32 v[16:17], v[14:15]
	s_lshl_b32 s29, s29, 8
	v_cmp_gt_u32_e64 s[40:41], 32, v184
	v_lshl_add_u32 v208, v183, 2, v187
	v_lshlrev_b32_e32 v207, 4, v175
	v_add_u32_e32 v176, 0x6000, v174
	v_mov_b32_e32 v209, 0
	s_mov_b32 s30, -1
	v_mov_b64_e32 v[14:15], v[12:13]
	v_mov_b64_e32 v[12:13], v[10:11]
	v_mov_b64_e32 v[10:11], v[8:9]
	v_mov_b64_e32 v[8:9], v[6:7]
	v_mov_b64_e32 v[6:7], v[4:5]
	v_mov_b64_e32 v[4:5], v[2:3]
	v_mov_b64_e32 v[2:3], v[0:1]
	v_add_u32_e32 v176, 0xffffe000, v176
	v_add_u32_e32 v178, 0xfffe0000, v178
	s_mov_b64 s[98:99], s[12:13]
	v_subrev_u32_e32 v180, s12, v180
	v_sub_f32_e32 v230, 0x40e00000, v217
	v_mov_b32_e32 v231, v230
	v_mov_b32_e32 v232, v230
	v_mov_b32_e32 v233, v230
	v_mov_b32_e32 v234, v230
	v_mov_b32_e32 v235, v230
	v_mov_b32_e32 v236, v230
	v_mov_b32_e32 v237, v230
	v_mov_b32_e32 v238, v230
	v_mov_b32_e32 v239, v230
	v_mov_b32_e32 v240, v230
	v_mov_b32_e32 v241, v230
	v_mov_b32_e32 v242, v230
	v_mov_b32_e32 v243, v230
	v_mov_b32_e32 v244, v230
	v_mov_b32_e32 v245, v230
	s_waitcnt lgkmcnt(0)
	s_barrier
.LBB0_1321:
	global_load_dwordx4 v[158:161], v176, s[18:19]
	global_load_dwordx4 v[162:165], v178, s[16:17]
	s_cmp_lg_u64 s[42:43], 0
	s_cbranch_scc0 .Lmla_A_nokr
	global_load_dwordx4 v[154:157], v180, s[98:99]
.Lmla_A_nokr:
	ds_read_b128 v[114:117], v215 offset:24576
	ds_read_b128 v[118:121], v216 offset:24576
	ds_read_b128 v[222:225], v215 offset:28672
	ds_read_b128 v[226:229], v216 offset:28672
	v_exp_f32_e32 v0, v82
	v_exp_f32_e32 v177, v83
	v_exp_f32_e32 v179, v84
	v_exp_f32_e32 v254, v85
	v_add_f32_e32 v219, v0, v177
	v_cvt_pk_fp8_f32 v246, v0, v177
	v_add_f32_e32 v219, v179, v219
	v_add_f32_e32 v219, v254, v219
	v_cvt_pk_fp8_f32 v246, v179, v254 op_sel:[0,0,1]
	s_waitcnt lgkmcnt(2)
	v_mfma_scale_f32_32x32x64_f8f6f4 v[114:129], v[114:121], v[146:153], v[230:245], v194, v193 op_sel_hi:[0,0,0]
	v_exp_f32_e32 v0, v86
	v_exp_f32_e32 v177, v87
	v_exp_f32_e32 v179, v88
	v_exp_f32_e32 v254, v89
	v_add_f32_e32 v219, v0, v219
	v_add_f32_e32 v219, v177, v219
	v_cvt_pk_fp8_f32 v247, v0, v177
	v_add_f32_e32 v219, v179, v219
	v_add_f32_e32 v219, v254, v219
	v_cvt_pk_fp8_f32 v247, v179, v254 op_sel:[0,0,1]
	ds_read_b128 v[82:85], v213 offset:24576
	ds_read_b128 v[86:89], v214 offset:24576
	s_waitcnt lgkmcnt(2)
	v_mfma_scale_f32_32x32x64_f8f6f4 v[98:113], v[222:229], v[146:153], v[230:245], v194, v193 op_sel_hi:[0,0,0]
	ds_read_b128 v[222:225], v213 offset:28672
	ds_read_b128 v[226:229], v214 offset:28672
	v_exp_f32_e32 v0, v90
	v_exp_f32_e32 v177, v91
	v_exp_f32_e32 v179, v92
	v_exp_f32_e32 v254, v93
	v_add_f32_e32 v219, v0, v219
	v_add_f32_e32 v219, v177, v219
	v_cvt_pk_fp8_f32 v248, v0, v177
	v_add_f32_e32 v219, v179, v219
	v_add_f32_e32 v219, v254, v219
	v_cvt_pk_fp8_f32 v248, v179, v254 op_sel:[0,0,1]
	v_exp_f32_e32 v0, v94
	v_exp_f32_e32 v177, v95
	v_exp_f32_e32 v179, v96
	v_exp_f32_e32 v254, v97
	v_add_f32_e32 v219, v0, v219
	v_add_f32_e32 v219, v177, v219
	v_cvt_pk_fp8_f32 v249, v0, v177
	v_add_f32_e32 v219, v179, v219
	v_add_f32_e32 v219, v254, v219
	v_cvt_pk_fp8_f32 v249, v179, v254 op_sel:[0,0,1]
	ds_read_b128 v[90:93], v185 offset:36864
	ds_read_b128 v[94:97], v186 offset:36864
	s_waitcnt lgkmcnt(4)
	v_mfma_scale_f32_32x32x64_f8f6f4 v[114:129], v[82:89], v[138:145], v[114:129], v194, v193 op_sel_hi:[0,0,0]
	v_exp_f32_e32 v0, v66
	v_exp_f32_e32 v177, v67
	v_exp_f32_e32 v179, v68
	v_exp_f32_e32 v254, v69
	v_add_f32_e32 v219, v0, v219
	v_add_f32_e32 v219, v177, v219
	v_cvt_pk_fp8_f32 v250, v0, v177
	v_add_f32_e32 v219, v179, v219
	v_add_f32_e32 v219, v254, v219
	v_cvt_pk_fp8_f32 v250, v179, v254 op_sel:[0,0,1]
	s_waitcnt lgkmcnt(2)
	v_mfma_scale_f32_32x32x64_f8f6f4 v[98:113], v[222:229], v[138:145], v[98:113], v194, v193 op_sel_hi:[0,0,0]
	ds_read_b128 v[222:225], v185 offset:38912
	ds_read_b128 v[226:229], v186 offset:38912
	v_exp_f32_e32 v0, v70
	v_exp_f32_e32 v177, v71
	v_exp_f32_e32 v179, v72
	v_exp_f32_e32 v254, v73
	v_add_f32_e32 v219, v0, v219
	v_add_f32_e32 v219, v177, v219
	v_cvt_pk_fp8_f32 v251, v0, v177
	v_add_f32_e32 v219, v179, v219
	v_add_f32_e32 v219, v254, v219
	v_cvt_pk_fp8_f32 v251, v179, v254 op_sel:[0,0,1]
	v_exp_f32_e32 v0, v74
	v_exp_f32_e32 v177, v75
	v_exp_f32_e32 v179, v76
	v_exp_f32_e32 v254, v77
	v_add_f32_e32 v219, v0, v219
	v_add_f32_e32 v219, v177, v219
	v_cvt_pk_fp8_f32 v252, v0, v177
	v_add_f32_e32 v219, v179, v219
	v_add_f32_e32 v219, v254, v219
	v_cvt_pk_fp8_f32 v252, v179, v254 op_sel:[0,0,1]
	s_waitcnt lgkmcnt(2)
; __device__ __forceinline__ void pv8(f32x16* o, const char* Vt, const v8i32 p8, int r32, int hi) {
;   const int sw = (r32 >> 2) & 3, a0 = r32 * 64 + (((hi * 2) ^ sw) << 4), a1 = r32 * 64 + (((hi * 2 + 1) ^ sw) << 4);
; #pragma unroll
;   for (int d0 = 0; d0 < 4; ++d0) {
;     const v8i32 vf = cat8(*reinterpret_cast<const v4i32*>(Vt + d0 * 2048 + a0), *reinterpret_cast<const v4i32*>(Vt + d0 * 2048 + a1));
;     o[d0] = __builtin_amdgcn_mfma_scale_f32_32x32x64_f8f6f4(p8, vf, o[d0], 0, 0, 0, 127, 0, 127); }
; }
; __device__ __forceinline__ void qkt9(f32x16& p0, f32x16& p1, const char* Kn, const char* Kr, const v8i32* qf, const float init, int r32, int hi) {
; #pragma unroll
;   for (int r = 0; r < 16; ++r) { p0[r] = init; p1[r] = init; }
; #pragma unroll
;   for (int s = 0; s < 2; ++s) { const int c0 = s * 4 + hi * 2;
;     const v8i32 a0 = cat8(*reinterpret_cast<const v4i32*>(Kn + KN8SW(r32, c0)), *reinterpret_cast<const v4i32*>(Kn + KN8SW(r32, c0 + 1)));
;     const v8i32 a1 = cat8(*reinterpret_cast<const v4i32*>(Kn + 4096 + KN8SW(r32, c0)), *reinterpret_cast<const v4i32*>(Kn + 4096 + KN8SW(r32, c0 + 1)));
;     p0 = __builtin_amdgcn_mfma_scale_f32_32x32x64_f8f6f4(a0, qf[s], p0, 0, 0, 0, 127, 0, 124);
;     p1 = __builtin_amdgcn_mfma_scale_f32_32x32x64_f8f6f4(a1, qf[s], p1, 0, 0, 0, 127, 0, 124); }
;   { const int c0 = hi * 2;
;     const v8i32 a0 = cat8(*reinterpret_cast<const v4i32*>(Kr + KR8SW(r32, c0)), *reinterpret_cast<const v4i32*>(Kr + KR8SW(r32, c0 + 1)));
;     const v8i32 a1 = cat8(*reinterpret_cast<const v4i32*>(Kr + 2048 + KR8SW(r32, c0)), *reinterpret_cast<const v4i32*>(Kr + 2048 + KR8SW(r32, c0 + 1)));
;     p0 = __builtin_amdgcn_mfma_scale_f32_32x32x64_f8f6f4(a0, qf[2], p0, 0, 0, 0, 127, 0, 124);
;     p1 = __builtin_amdgcn_mfma_scale_f32_32x32x64_f8f6f4(a1, qf[2], p1, 0, 0, 0, 127, 0, 124); }
; }
; __device__ __forceinline__ void partialSM9(f32x16& p0, f32x16& p1, float& m_run, float& alpha, const float thr2) {
;   float pmax = p0[0];
; #pragma unroll
;   for (int r = 1; r < 16; ++r) pmax = fmaxf(pmax, p0[r]);
; __device__ __forceinline__ void attn_unit7(const unsigned char* __restrict__ Q8, int ldq, const unsigned char* __restrict__ Kn8, int ldk, const unsigned char* __restrict__ Kr8, ...
;     ...
;     pv8(o, Vt_lds, p8, r32, hi); partialSM9(pB0, pB1, m_reg, alB, thr_raw);
;     __syncthreads(); SWRITE(0);
;     RESC(alB); __syncthreads();
	v_mfma_scale_f32_32x32x64_f8f6f4 v[114:129], v[90:97], v[130:137], v[114:129], v194, v193 op_sel_hi:[0,0,0]
	v_exp_f32_e32 v0, v78
	v_exp_f32_e32 v177, v79
	v_exp_f32_e32 v179, v80
	v_exp_f32_e32 v254, v81
	v_add_f32_e32 v219, v0, v219
	v_add_f32_e32 v219, v177, v219
	v_cvt_pk_fp8_f32 v253, v0, v177
	v_add_f32_e32 v219, v179, v219
	v_add_f32_e32 v219, v254, v219
	v_cvt_pk_fp8_f32 v253, v179, v254 op_sel:[0,0,1]
	ds_read_b128 v[90:93], v185 offset:0
	ds_read_b128 v[94:97], v186 offset:0
	ds_read_b128 v[82:85], v185 offset:2048
	ds_read_b128 v[86:89], v186 offset:2048
	ds_read_b128 v[74:77], v185 offset:4096
	ds_read_b128 v[78:81], v186 offset:4096
	ds_read_b128 v[66:69], v185 offset:6144
	ds_read_b128 v[70:73], v186 offset:6144
	s_waitcnt lgkmcnt(8)
	v_mfma_scale_f32_32x32x64_f8f6f4 v[98:113], v[222:229], v[130:137], v[98:113], v194, v193 op_sel_hi:[0,0,0]
	v_fma_f32 v209, v209, v218, v219
	v_max_f32_e32 v177, v114, v115
	v_max3_f32 v177, v177, v116, v117
	v_max3_f32 v177, v177, v118, v119
	v_max3_f32 v177, v177, v120, v121
	v_max3_f32 v177, v177, v122, v123
	v_max3_f32 v177, v177, v124, v125
	v_max3_f32 v177, v177, v126, v127
	v_max3_f32 v177, v177, v128, v129
	s_waitcnt lgkmcnt(4)
	v_mfma_scale_f32_32x32x64_f8f6f4 v[50:65], v[246:253], v[90:97], v[50:65], v194, v194 op_sel_hi:[0,0,0]
	v_mfma_scale_f32_32x32x64_f8f6f4 v[34:49], v[246:253], v[82:89], v[34:49], v194, v194 op_sel_hi:[0,0,0]
	s_waitcnt lgkmcnt(0)
	v_mfma_scale_f32_32x32x64_f8f6f4 v[18:33], v[246:253], v[74:81], v[18:33], v194, v194 op_sel_hi:[0,0,0]
	v_mfma_scale_f32_32x32x64_f8f6f4 v[2:17], v[246:253], v[66:73], v[2:17], v194, v194 op_sel_hi:[0,0,0]
	v_add_u32_e32 v176, 0x2000, v176
	v_add_u32_e32 v178, 0x20000, v178
	s_add_u32 s98, s98, 0x1000
	s_addc_u32 s99, s99, 0
	v_mov_b32_e32 v221, 1.0
	v_max_f32_e32 v0, v98, v99
	v_max3_f32 v0, v0, v100, v101
	v_max3_f32 v0, v0, v102, v103
	v_max3_f32 v0, v0, v104, v105
	v_max3_f32 v0, v0, v106, v107
	v_max3_f32 v0, v0, v108, v109
	v_max3_f32 v0, v0, v110, v111
	v_max3_f32 v0, v0, v112, v113
	v_max_f32_e32 v177, v177, v0
	v_cmp_ge_f32_e32 vcc, s90, v177
	s_cmp_eq_u64 vcc, exec
	s_cbranch_scc0 .Lmla_A_newmax
	s_barrier
	s_waitcnt vmcnt(0)
	ds_write_b128 v210, v[158:161]
	ds_write_b128 v211, v[162:165] offset:16384
	s_and_saveexec_b64 s[20:21], s[42:43]
	ds_write_b128 v212, v[154:157] offset:32768
	s_or_b64 exec, exec, s[20:21]
.Lmla_A_resc_done:
	s_waitcnt lgkmcnt(0)
	s_barrier
	global_load_dwordx4 v[158:161], v176, s[18:19]
	global_load_dwordx4 v[162:165], v178, s[16:17]
	s_cmp_lg_u64 s[42:43], 0
	s_cbranch_scc0 .Lmla_B_nokr
	global_load_dwordx4 v[154:157], v180, s[98:99]
.Lmla_B_nokr:
	ds_read_b128 v[82:85], v215 offset:16384
	ds_read_b128 v[86:89], v216 offset:16384
	ds_read_b128 v[222:225], v215 offset:20480
	ds_read_b128 v[226:229], v216 offset:20480
	v_exp_f32_e32 v0, v114
	v_exp_f32_e32 v177, v115
	v_exp_f32_e32 v179, v116
	v_exp_f32_e32 v254, v117
	v_add_f32_e32 v219, v0, v177
	v_cvt_pk_fp8_f32 v246, v0, v177
	v_add_f32_e32 v219, v179, v219
	v_add_f32_e32 v219, v254, v219
	v_cvt_pk_fp8_f32 v246, v179, v254 op_sel:[0,0,1]
	s_waitcnt lgkmcnt(2)
	v_mfma_scale_f32_32x32x64_f8f6f4 v[82:97], v[82:89], v[146:153], v[230:245], v194, v193 op_sel_hi:[0,0,0]
	v_exp_f32_e32 v0, v118
	v_exp_f32_e32 v177, v119
	v_exp_f32_e32 v179, v120
	v_exp_f32_e32 v254, v121
	v_add_f32_e32 v219, v0, v219
	v_add_f32_e32 v219, v177, v219
	v_cvt_pk_fp8_f32 v247, v0, v177
	v_add_f32_e32 v219, v179, v219
	v_add_f32_e32 v219, v254, v219
	v_cvt_pk_fp8_f32 v247, v179, v254 op_sel:[0,0,1]
	ds_read_b128 v[114:117], v213 offset:16384
	ds_read_b128 v[118:121], v214 offset:16384
	s_waitcnt lgkmcnt(2)
	v_mfma_scale_f32_32x32x64_f8f6f4 v[66:81], v[222:229], v[146:153], v[230:245], v194, v193 op_sel_hi:[0,0,0]
	ds_read_b128 v[222:225], v213 offset:20480
	ds_read_b128 v[226:229], v214 offset:20480
	v_exp_f32_e32 v0, v122
	v_exp_f32_e32 v177, v123
	v_exp_f32_e32 v179, v124
	v_exp_f32_e32 v254, v125
	v_add_f32_e32 v219, v0, v219
	v_add_f32_e32 v219, v177, v219
	v_cvt_pk_fp8_f32 v248, v0, v177
	v_add_f32_e32 v219, v179, v219
	v_add_f32_e32 v219, v254, v219
	v_cvt_pk_fp8_f32 v248, v179, v254 op_sel:[0,0,1]
	v_exp_f32_e32 v0, v126
	v_exp_f32_e32 v177, v127
	v_exp_f32_e32 v179, v128
	v_exp_f32_e32 v254, v129
	v_add_f32_e32 v219, v0, v219
	v_add_f32_e32 v219, v177, v219
	v_cvt_pk_fp8_f32 v249, v0, v177
	v_add_f32_e32 v219, v179, v219
	v_add_f32_e32 v219, v254, v219
	v_cvt_pk_fp8_f32 v249, v179, v254 op_sel:[0,0,1]
	ds_read_b128 v[122:125], v185 offset:32768
	ds_read_b128 v[126:129], v186 offset:32768
	s_waitcnt lgkmcnt(4)
	v_mfma_scale_f32_32x32x64_f8f6f4 v[82:97], v[114:121], v[138:145], v[82:97], v194, v193 op_sel_hi:[0,0,0]
	v_exp_f32_e32 v0, v98
	v_exp_f32_e32 v177, v99
	v_exp_f32_e32 v179, v100
	v_exp_f32_e32 v254, v101
	v_add_f32_e32 v219, v0, v219
	v_add_f32_e32 v219, v177, v219
	v_cvt_pk_fp8_f32 v250, v0, v177
	v_add_f32_e32 v219, v179, v219
	v_add_f32_e32 v219, v254, v219
	v_cvt_pk_fp8_f32 v250, v179, v254 op_sel:[0,0,1]
	s_waitcnt lgkmcnt(2)
	v_mfma_scale_f32_32x32x64_f8f6f4 v[66:81], v[222:229], v[138:145], v[66:81], v194, v193 op_sel_hi:[0,0,0]
	ds_read_b128 v[222:225], v185 offset:34816
	ds_read_b128 v[226:229], v186 offset:34816
	v_exp_f32_e32 v0, v102
	v_exp_f32_e32 v177, v103
	v_exp_f32_e32 v179, v104
	v_exp_f32_e32 v254, v105
	v_add_f32_e32 v219, v0, v219
	v_add_f32_e32 v219, v177, v219
	v_cvt_pk_fp8_f32 v251, v0, v177
	v_add_f32_e32 v219, v179, v219
	v_add_f32_e32 v219, v254, v219
	v_cvt_pk_fp8_f32 v251, v179, v254 op_sel:[0,0,1]
	v_exp_f32_e32 v0, v106
	v_exp_f32_e32 v177, v107
	v_exp_f32_e32 v179, v108
	v_exp_f32_e32 v254, v109
	v_add_f32_e32 v219, v0, v219
	v_add_f32_e32 v219, v177, v219
	v_cvt_pk_fp8_f32 v252, v0, v177
	v_add_f32_e32 v219, v179, v219
	v_add_f32_e32 v219, v254, v219
	v_cvt_pk_fp8_f32 v252, v179, v254 op_sel:[0,0,1]
	s_waitcnt lgkmcnt(2)
; #define SWRITE(b) do { *(bf16x8*)(V_lds + (b) * SHM_V + vst0) = vs0; *(bf16x8*)(V_lds + (b) * SHM_V + vst1) = vs1; const int kc = sc * 2;  \
;     *(bf16x8*)(K_lds + (b) * SHM_K + KSWZ(sr, kc)) = ks0; *(bf16x8*)(K_lds + (b) * SHM_K + KSWZ(32 + sr, kc)) = ks1; \
;     if constexpr (NR > 0) *(bf16x8*)(Kr_lds + (b) * SHM_KR + krst) = kr; } while (0)
; #define SWRITE(b) do { *(bf16x8*)(V_lds + (b) * SHM_V + vst0) = vs0; *(bf16x8*)(V_lds + (b) * SHM_V + vst0 + 8192) = vs1;  \
;     *(bf16x8*)(K_lds + (b) * SHM_K + kst0) = ks0; *(bf16x8*)(K_lds + (b) * SHM_K + kst0 + 8192) = ks1; \
;     if constexpr (NR > 0) *(bf16x8*)(Kr_lds + (b) * SHM_KR + krst) = kr; } while (0)
; #define RESC(a) do { if (__any((a) < 1.f)) { if (hi == 0) al_l[r32] = (a); asm volatile("s_waitcnt lgkmcnt(0)" ::: "memory"); \
;     _Pragma("unroll") for (int d = 0; d < 4; ++d) _Pragma("unroll") for (int r = 0; r < 16; ++r) o[d][r] *= al_l[crow(r, hi)]; } } while (0)
; #define SWRITE(b) do { *(bf16x8*)(V_lds + (b) * 16384 + vst0) = vs0; *(bf16x8*)(V_lds + (b) * 16384 + vst0 + 8192) = vs1;  \
;     *(v4i32*)(Kn_lds + (b) * 8192 + knst) = kn; if (krw) *(v4i32*)(Kr_lds + (b) * 4096 + krst) = kr; } while (0)
; __device__ __forceinline__ void partialSM9(f32x16& p0, f32x16& p1, float& m_run, float& alpha, const float thr2) {
;   float pmax = p0[0];
; #pragma unroll
;   for (int r = 1; r < 16; ++r) pmax = fmaxf(pmax, p0[r]);
; #pragma unroll
;   for (int r = 0; r < 16; ++r) pmax = fmaxf(pmax, p1[r]);
;   { auto rr = __builtin_amdgcn_permlane32_swap(__float_as_uint(pmax), __float_as_uint(pmax), false, false);
;     pmax = fmaxf(__uint_as_float(rr[0]), __uint_as_float(rr[1])); }
;   if (__builtin_expect(__all(pmax <= 7.0f + thr2), 1)) { alpha = 1.f; }
;   else { const float delta = fmaxf(pmax - 7.0f, 0.f); alpha = __builtin_amdgcn_exp2f(-delta); m_run += delta;
; #pragma unroll
;     for (int r = 0; r < 16; ++r) { p0[r] -= delta; p1[r] -= delta; } }
; }
; __device__ __forceinline__ void attn_unit7(const unsigned char* __restrict__ Q8, int ldq, const unsigned char* __restrict__ Kn8, int ldk, const unsigned char* __restrict__ Kr8, ...
;     ...
;     pv8(o, Vt_lds + 8192, p8, r32, hi); partialSM9(pA0, pA1, m_reg, alA, thr_raw);
;     __syncthreads(); if (j + 2 < NT) SWRITE(1);
;     RESC(alA); __syncthreads();
;   }
	v_mfma_scale_f32_32x32x64_f8f6f4 v[82:97], v[122:129], v[130:137], v[82:97], v194, v193 op_sel_hi:[0,0,0]
	v_exp_f32_e32 v0, v110
	v_exp_f32_e32 v177, v111
	v_exp_f32_e32 v179, v112
	v_exp_f32_e32 v254, v113
	v_add_f32_e32 v219, v0, v219
	v_add_f32_e32 v219, v177, v219
	v_cvt_pk_fp8_f32 v253, v0, v177
	v_add_f32_e32 v219, v179, v219
	v_add_f32_e32 v219, v254, v219
	v_cvt_pk_fp8_f32 v253, v179, v254 op_sel:[0,0,1]
	ds_read_b128 v[122:125], v185 offset:8192
	ds_read_b128 v[126:129], v186 offset:8192
	ds_read_b128 v[114:117], v185 offset:10240
	ds_read_b128 v[118:121], v186 offset:10240
	ds_read_b128 v[106:109], v185 offset:12288
	ds_read_b128 v[110:113], v186 offset:12288
	ds_read_b128 v[98:101], v185 offset:14336
	ds_read_b128 v[102:105], v186 offset:14336
	s_waitcnt lgkmcnt(8)
	v_mfma_scale_f32_32x32x64_f8f6f4 v[66:81], v[222:229], v[130:137], v[66:81], v194, v193 op_sel_hi:[0,0,0]
	v_fma_f32 v209, v209, v221, v219
	v_max_f32_e32 v177, v82, v83
	v_max3_f32 v177, v177, v84, v85
	v_max3_f32 v177, v177, v86, v87
	v_max3_f32 v177, v177, v88, v89
	v_max3_f32 v177, v177, v90, v91
	v_max3_f32 v177, v177, v92, v93
	v_max3_f32 v177, v177, v94, v95
	v_max3_f32 v177, v177, v96, v97
	s_waitcnt lgkmcnt(4)
	v_mfma_scale_f32_32x32x64_f8f6f4 v[50:65], v[246:253], v[122:129], v[50:65], v194, v194 op_sel_hi:[0,0,0]
	v_mfma_scale_f32_32x32x64_f8f6f4 v[34:49], v[246:253], v[114:121], v[34:49], v194, v194 op_sel_hi:[0,0,0]
	s_waitcnt lgkmcnt(0)
	v_mfma_scale_f32_32x32x64_f8f6f4 v[18:33], v[246:253], v[106:113], v[18:33], v194, v194 op_sel_hi:[0,0,0]
	v_mfma_scale_f32_32x32x64_f8f6f4 v[2:17], v[246:253], v[98:105], v[2:17], v194, v194 op_sel_hi:[0,0,0]
	v_add_u32_e32 v176, 0x2000, v176
	v_add_u32_e32 v178, 0x20000, v178
	s_add_u32 s98, s98, 0x1000
	s_addc_u32 s99, s99, 0
	v_mov_b32_e32 v218, 1.0
	v_max_f32_e32 v0, v66, v67
	v_max3_f32 v0, v0, v68, v69
	v_max3_f32 v0, v0, v70, v71
	v_max3_f32 v0, v0, v72, v73
	v_max3_f32 v0, v0, v74, v75
	v_max3_f32 v0, v0, v76, v77
	v_max3_f32 v0, v0, v78, v79
	v_max3_f32 v0, v0, v80, v81
	v_max_f32_e32 v177, v177, v0
	v_cmp_ge_f32_e32 vcc, s90, v177
	s_cmp_eq_u64 vcc, exec
	s_cbranch_scc0 .Lmla_B_newmax
	s_barrier
	s_waitcnt vmcnt(0)
	ds_write_b128 v210, v[158:161] offset:8192
	ds_write_b128 v211, v[162:165] offset:24576
	s_and_saveexec_b64 s[20:21], s[42:43]
	ds_write_b128 v212, v[154:157] offset:36864
	s_or_b64 exec, exec, s[20:21]
.Lmla_B_resc_done:
	s_add_i32 s30, s30, 2
	v_mov_b32_e32 v0, v218
	s_waitcnt lgkmcnt(0)
	s_barrier
	s_cmpk_gt_u32 s30, 0xfc
	s_cbranch_scc0 .LBB0_1321
	v_mov_b32_e32 v177, v209
	s_nop 1
	v_permlane32_swap_b32_e32 v209, v177
	v_add_f32_e32 v209, v209, v177
	s_branch .LBB0_1343
.Lmla_A_newmax:
	v_mov_b32_e32 v0, v177
	s_nop 1
	v_permlane32_swap_b32_e32 v177, v0
	v_max_f32_e32 v177, v177, v0
	v_add_f32_e32 v0, 0xc0e00000, v177
	v_max_f32_e32 v177, 0, v0
	v_exp_f32_e64 v221, -v177
	v_add_f32_e32 v217, v217, v177
	v_sub_f32_e32 v129, v129, v177
	v_sub_f32_e32 v128, v128, v177
	v_sub_f32_e32 v127, v127, v177
	v_sub_f32_e32 v126, v126, v177
	v_sub_f32_e32 v125, v125, v177
	v_sub_f32_e32 v124, v124, v177
	v_sub_f32_e32 v123, v123, v177
	v_sub_f32_e32 v122, v122, v177
	v_sub_f32_e32 v121, v121, v177
	v_sub_f32_e32 v120, v120, v177
	v_sub_f32_e32 v119, v119, v177
	v_sub_f32_e32 v118, v118, v177
	v_sub_f32_e32 v117, v117, v177
	v_sub_f32_e32 v116, v116, v177
	v_sub_f32_e32 v115, v115, v177
	v_sub_f32_e32 v114, v114, v177
	v_sub_f32_e32 v113, v113, v177
	v_sub_f32_e32 v112, v112, v177
	v_sub_f32_e32 v111, v111, v177
	v_sub_f32_e32 v110, v110, v177
	v_sub_f32_e32 v109, v109, v177
	v_sub_f32_e32 v108, v108, v177
	v_sub_f32_e32 v107, v107, v177
	v_sub_f32_e32 v106, v106, v177
	v_sub_f32_e32 v105, v105, v177
	v_sub_f32_e32 v104, v104, v177
	v_sub_f32_e32 v103, v103, v177
	v_sub_f32_e32 v102, v102, v177
	v_sub_f32_e32 v101, v101, v177
	v_sub_f32_e32 v100, v100, v177
	v_sub_f32_e32 v99, v99, v177
	v_sub_f32_e32 v98, v98, v177
	v_sub_f32_e32 v230, 0x40e00000, v217
	v_mov_b32_e32 v231, v230
	v_mov_b32_e32 v232, v230
	v_mov_b32_e32 v233, v230
	v_mov_b32_e32 v234, v230
	v_mov_b32_e32 v235, v230
	v_mov_b32_e32 v236, v230
	v_mov_b32_e32 v237, v230
	v_mov_b32_e32 v238, v230
	v_mov_b32_e32 v239, v230
	v_mov_b32_e32 v240, v230
	v_mov_b32_e32 v241, v230
	v_mov_b32_e32 v242, v230
	v_mov_b32_e32 v243, v230
	v_mov_b32_e32 v244, v230
	v_mov_b32_e32 v245, v230
	s_barrier
	s_waitcnt vmcnt(0)
	ds_write_b128 v210, v[158:161]
	ds_write_b128 v211, v[162:165] offset:16384
	s_and_saveexec_b64 s[20:21], s[42:43]
	ds_write_b128 v212, v[154:157] offset:32768
	s_or_b64 exec, exec, s[20:21]
	s_and_saveexec_b64 s[20:21], s[40:41]
	ds_write_b32 v208, v221 offset:41088
	s_or_b64 exec, exec, s[20:21]
	v_add_u32_e32 v0, v187, v207
	s_waitcnt lgkmcnt(0)
	ds_read_b128 v[66:69], v0 offset:41184
	ds_read_b128 v[70:73], v0 offset:41152
	ds_read_b128 v[74:77], v0 offset:41120
	ds_read_b128 v[78:81], v0 offset:41088
	s_nop 15
	s_nop 7
	s_waitcnt lgkmcnt(0)
	v_pk_mul_f32 v[62:63], v[62:63], v[66:67]
	v_pk_mul_f32 v[58:59], v[58:59], v[70:71]
	v_pk_mul_f32 v[54:55], v[54:55], v[74:75]
	v_pk_mul_f32 v[64:65], v[64:65], v[68:69]
	v_pk_mul_f32 v[60:61], v[60:61], v[72:73]
	v_pk_mul_f32 v[56:57], v[56:57], v[76:77]
	v_pk_mul_f32 v[52:53], v[52:53], v[80:81]
	v_pk_mul_f32 v[50:51], v[50:51], v[78:79]
	v_pk_mul_f32 v[46:47], v[46:47], v[66:67]
	v_pk_mul_f32 v[42:43], v[42:43], v[70:71]
	v_pk_mul_f32 v[38:39], v[38:39], v[74:75]
	v_pk_mul_f32 v[48:49], v[48:49], v[68:69]
	v_pk_mul_f32 v[44:45], v[44:45], v[72:73]
	v_pk_mul_f32 v[40:41], v[40:41], v[76:77]
	v_pk_mul_f32 v[36:37], v[36:37], v[80:81]
	v_pk_mul_f32 v[34:35], v[34:35], v[78:79]
	v_pk_mul_f32 v[30:31], v[30:31], v[66:67]
	v_pk_mul_f32 v[26:27], v[26:27], v[70:71]
	v_pk_mul_f32 v[22:23], v[22:23], v[74:75]
	v_pk_mul_f32 v[32:33], v[32:33], v[68:69]
	v_pk_mul_f32 v[28:29], v[28:29], v[72:73]
	v_pk_mul_f32 v[24:25], v[24:25], v[76:77]
	v_pk_mul_f32 v[20:21], v[20:21], v[80:81]
	v_pk_mul_f32 v[18:19], v[18:19], v[78:79]
	v_pk_mul_f32 v[14:15], v[14:15], v[66:67]
	v_pk_mul_f32 v[10:11], v[10:11], v[70:71]
	v_pk_mul_f32 v[6:7], v[6:7], v[74:75]
	v_pk_mul_f32 v[16:17], v[16:17], v[68:69]
	v_pk_mul_f32 v[12:13], v[12:13], v[72:73]
	v_pk_mul_f32 v[8:9], v[8:9], v[76:77]
	v_pk_mul_f32 v[4:5], v[4:5], v[80:81]
	v_pk_mul_f32 v[2:3], v[2:3], v[78:79]
	s_branch .Lmla_A_resc_done
; #define SWRITE(b) do { *(bf16x8*)(V_lds + (b) * SHM_V + vst0) = vs0; *(bf16x8*)(V_lds + (b) * SHM_V + vst1) = vs1; const int kc = sc * 2;  \
;     *(bf16x8*)(K_lds + (b) * SHM_K + KSWZ(sr, kc)) = ks0; *(bf16x8*)(K_lds + (b) * SHM_K + KSWZ(32 + sr, kc)) = ks1; \
;     if constexpr (NR > 0) *(bf16x8*)(Kr_lds + (b) * SHM_KR + krst) = kr; } while (0)
; #define SWRITE(b) do { *(bf16x8*)(V_lds + (b) * SHM_V + vst0) = vs0; *(bf16x8*)(V_lds + (b) * SHM_V + vst0 + 8192) = vs1;  \
;     *(bf16x8*)(K_lds + (b) * SHM_K + kst0) = ks0; *(bf16x8*)(K_lds + (b) * SHM_K + kst0 + 8192) = ks1; \
;     if constexpr (NR > 0) *(bf16x8*)(Kr_lds + (b) * SHM_KR + krst) = kr; } while (0)
; #define RESC(a) do { if (__any((a) < 1.f)) { if (hi == 0) al_l[r32] = (a); asm volatile("s_waitcnt lgkmcnt(0)" ::: "memory"); \
;     _Pragma("unroll") for (int d = 0; d < 4; ++d) _Pragma("unroll") for (int r = 0; r < 16; ++r) o[d][r] *= al_l[crow(r, hi)]; } } while (0)
; #define SWRITE(b) do { *(bf16x8*)(V_lds + (b) * 16384 + vst0) = vs0; *(bf16x8*)(V_lds + (b) * 16384 + vst0 + 8192) = vs1;  \
;     *(v4i32*)(Kn_lds + (b) * 8192 + knst) = kn; if (krw) *(v4i32*)(Kr_lds + (b) * 4096 + krst) = kr; } while (0)
; #define RESC(a) do { if (__any((a) < 1.f)) { if (hi == 0) al_l[r32] = (a); asm volatile("s_waitcnt lgkmcnt(0)" ::: "memory"); \
;     _Pragma("unroll") for (int d = 0; d < 4; ++d) _Pragma("unroll") for (int r = 0; r < 16; ++r) o[d][r] *= al_l[crow(r, hi)]; } } while (0)
; #define SWRITE(b) do { *(v4i32*)(Vt_lds + (b) * 8192 + vtst) = vt; *(v4i32*)(Kn_lds + (b) * 8192 + knst) = kn; if (krw) *(v4i32*)(Kr_lds + (b) * 4096 + krst) = kr; } while (0)
; __device__ __forceinline__ void partialSM9(f32x16& p0, f32x16& p1, float& m_run, float& alpha, const float thr2) {
;     ...
;     pmax = fmaxf(__uint_as_float(rr[0]), __uint_as_float(rr[1])); }
;   if (__builtin_expect(__all(pmax <= 7.0f + thr2), 1)) { alpha = 1.f; }
;   else { const float delta = fmaxf(pmax - 7.0f, 0.f); alpha = __builtin_amdgcn_exp2f(-delta); m_run += delta;
; #pragma unroll
;     for (int r = 0; r < 16; ++r) { p0[r] -= delta; p1[r] -= delta; } }
; }
; __device__ __forceinline__ void attn_unit7(const unsigned char* __restrict__ Q8, int ldq, const unsigned char* __restrict__ Kn8, int ldk, const unsigned char* __restrict__ Kr8, ...
;     ...
;     __syncthreads(); if (j + 2 < NT) SWRITE(1);
;     RESC(alA); __syncthreads();
.Lmla_B_newmax:
	v_mov_b32_e32 v0, v177
	s_nop 1
	v_permlane32_swap_b32_e32 v177, v0
	v_max_f32_e32 v177, v177, v0
	v_add_f32_e32 v0, 0xc0e00000, v177
	v_max_f32_e32 v177, 0, v0
	v_exp_f32_e64 v218, -v177
	v_add_f32_e32 v217, v217, v177
	v_sub_f32_e32 v97, v97, v177
	v_sub_f32_e32 v96, v96, v177
	v_sub_f32_e32 v95, v95, v177
	v_sub_f32_e32 v94, v94, v177
	v_sub_f32_e32 v93, v93, v177
	v_sub_f32_e32 v92, v92, v177
	v_sub_f32_e32 v91, v91, v177
	v_sub_f32_e32 v90, v90, v177
	v_sub_f32_e32 v89, v89, v177
	v_sub_f32_e32 v88, v88, v177
	v_sub_f32_e32 v87, v87, v177
	v_sub_f32_e32 v86, v86, v177
	v_sub_f32_e32 v85, v85, v177
	v_sub_f32_e32 v84, v84, v177
	v_sub_f32_e32 v83, v83, v177
	v_sub_f32_e32 v82, v82, v177
	v_sub_f32_e32 v81, v81, v177
	v_sub_f32_e32 v80, v80, v177
	v_sub_f32_e32 v79, v79, v177
	v_sub_f32_e32 v78, v78, v177
	v_sub_f32_e32 v77, v77, v177
	v_sub_f32_e32 v76, v76, v177
	v_sub_f32_e32 v75, v75, v177
	v_sub_f32_e32 v74, v74, v177
	v_sub_f32_e32 v73, v73, v177
	v_sub_f32_e32 v72, v72, v177
	v_sub_f32_e32 v71, v71, v177
	v_sub_f32_e32 v70, v70, v177
	v_sub_f32_e32 v69, v69, v177
	v_sub_f32_e32 v68, v68, v177
	v_sub_f32_e32 v67, v67, v177
	v_sub_f32_e32 v66, v66, v177
	v_sub_f32_e32 v230, 0x40e00000, v217
	v_mov_b32_e32 v231, v230
	v_mov_b32_e32 v232, v230
	v_mov_b32_e32 v233, v230
	v_mov_b32_e32 v234, v230
	v_mov_b32_e32 v235, v230
	v_mov_b32_e32 v236, v230
	v_mov_b32_e32 v237, v230
	v_mov_b32_e32 v238, v230
	v_mov_b32_e32 v239, v230
	v_mov_b32_e32 v240, v230
	v_mov_b32_e32 v241, v230
	v_mov_b32_e32 v242, v230
	v_mov_b32_e32 v243, v230
	v_mov_b32_e32 v244, v230
	v_mov_b32_e32 v245, v230
	s_barrier
	s_waitcnt vmcnt(0)
	ds_write_b128 v210, v[158:161] offset:8192
	ds_write_b128 v211, v[162:165] offset:24576
	s_and_saveexec_b64 s[20:21], s[42:43]
	ds_write_b128 v212, v[154:157] offset:36864
	s_or_b64 exec, exec, s[20:21]
	s_and_saveexec_b64 s[20:21], s[40:41]
	ds_write_b32 v208, v218 offset:41088
	s_or_b64 exec, exec, s[20:21]
	v_add_u32_e32 v0, v187, v207
	s_waitcnt lgkmcnt(0)
	ds_read_b128 v[98:101], v0 offset:41184
	ds_read_b128 v[102:105], v0 offset:41152
	ds_read_b128 v[106:109], v0 offset:41120
	ds_read_b128 v[110:113], v0 offset:41088
	s_nop 15
	s_nop 7
	s_waitcnt lgkmcnt(0)
	v_pk_mul_f32 v[62:63], v[62:63], v[98:99]
	v_pk_mul_f32 v[58:59], v[58:59], v[102:103]
	v_pk_mul_f32 v[54:55], v[54:55], v[106:107]
	v_pk_mul_f32 v[64:65], v[64:65], v[100:101]
	v_pk_mul_f32 v[60:61], v[60:61], v[104:105]
	v_pk_mul_f32 v[56:57], v[56:57], v[108:109]
	v_pk_mul_f32 v[52:53], v[52:53], v[112:113]
	v_pk_mul_f32 v[50:51], v[50:51], v[110:111]
	v_pk_mul_f32 v[46:47], v[46:47], v[98:99]
	v_pk_mul_f32 v[42:43], v[42:43], v[102:103]
	v_pk_mul_f32 v[38:39], v[38:39], v[106:107]
	v_pk_mul_f32 v[48:49], v[48:49], v[100:101]
	v_pk_mul_f32 v[44:45], v[44:45], v[104:105]
	v_pk_mul_f32 v[40:41], v[40:41], v[108:109]
	v_pk_mul_f32 v[36:37], v[36:37], v[112:113]
	v_pk_mul_f32 v[34:35], v[34:35], v[110:111]
	v_pk_mul_f32 v[30:31], v[30:31], v[98:99]
	v_pk_mul_f32 v[26:27], v[26:27], v[102:103]
	v_pk_mul_f32 v[22:23], v[22:23], v[106:107]
	v_pk_mul_f32 v[32:33], v[32:33], v[100:101]
	v_pk_mul_f32 v[28:29], v[28:29], v[104:105]
	v_pk_mul_f32 v[24:25], v[24:25], v[108:109]
	v_pk_mul_f32 v[20:21], v[20:21], v[112:113]
	v_pk_mul_f32 v[18:19], v[18:19], v[110:111]
	v_pk_mul_f32 v[14:15], v[14:15], v[98:99]
	v_pk_mul_f32 v[10:11], v[10:11], v[102:103]
	v_pk_mul_f32 v[6:7], v[6:7], v[106:107]
	v_pk_mul_f32 v[16:17], v[16:17], v[100:101]
	v_pk_mul_f32 v[12:13], v[12:13], v[104:105]
	v_pk_mul_f32 v[8:9], v[8:9], v[108:109]
	v_pk_mul_f32 v[4:5], v[4:5], v[112:113]
	v_pk_mul_f32 v[2:3], v[2:3], v[110:111]
	s_branch .Lmla_B_resc_done
